# v5 plus: layer-0 down-proj fused epilogue prefetches its bf16 residual with 16-byte loads (16 per lane instead of 32 x 8 B), un-permuted after the exchange barrier
# speedup vs baseline: 1.0217x; 1.0037x over previous
.LBB0_476:
	s_add_u32 s0, s16, 0x3000000
	s_addc_u32 s1, s17, 0
	s_lshl_b32 s3, s2, 5
	s_lshl_b32 s4, s18, 8
	s_or_b32 s3, s4, s3
	v_lshrrev_b32_e32 v126, 2, v146
	s_lshl_b32 s33, s31, 8
	v_and_or_b32 v150, v126, 12, s3
	s_add_i32 s3, s33, s30
	v_or_b32_e32 v126, s3, v217
	v_ashrrev_i32_e32 v151, 31, v150
	v_ashrrev_i32_e32 v127, 31, v126
	v_lshl_add_u64 v[128:129], v[150:151], 1, s[0:1]
	v_lshlrev_b64 v[130:131], 11, v[126:127]
	v_lshl_add_u64 v[130:131], v[128:129], 0, v[130:131]
	s_barrier
	v_mbcnt_lo_u32_b32 v238, -1, 0
	v_mbcnt_hi_u32_b32 v238, -1, v238
	v_lshrrev_b32_e32 v238, 4, v238
	v_lshlrev_b32_e32 v238, 3, v238
	v_mov_b32_e32 v239, 0
	v_lshl_add_u64 v[236:237], v[130:131], 0, v[238:239]
	global_load_dwordx4 v[212:215], v[236:237], off
	global_load_dwordx4 v[208:211], v[236:237], off offset:256
	v_or_b32_e32 v130, 16, v126
	v_ashrrev_i32_e32 v131, 31, v130
	v_lshlrev_b64 v[130:131], 11, v[130:131]
	v_lshl_add_u64 v[130:131], v[128:129], 0, v[130:131]
	v_lshl_add_u64 v[236:237], v[130:131], 0, v[238:239]
	global_load_dwordx4 v[204:207], v[236:237], off
	global_load_dwordx4 v[200:203], v[236:237], off offset:256
	v_or_b32_e32 v130, 32, v126
	v_ashrrev_i32_e32 v131, 31, v130
	v_lshlrev_b64 v[130:131], 11, v[130:131]
	v_lshl_add_u64 v[130:131], v[128:129], 0, v[130:131]
	v_lshl_add_u64 v[236:237], v[130:131], 0, v[238:239]
	global_load_dwordx4 v[196:199], v[236:237], off
	global_load_dwordx4 v[192:195], v[236:237], off offset:256
	v_or_b32_e32 v130, 48, v126
	v_ashrrev_i32_e32 v131, 31, v130
	v_lshlrev_b64 v[130:131], 11, v[130:131]
	v_lshl_add_u64 v[130:131], v[128:129], 0, v[130:131]
	v_lshl_add_u64 v[236:237], v[130:131], 0, v[238:239]
	global_load_dwordx4 v[188:191], v[236:237], off
	global_load_dwordx4 v[184:187], v[236:237], off offset:256
	v_add_u32_e32 v130, 0x80, v126
	v_ashrrev_i32_e32 v131, 31, v130
	v_lshlrev_b64 v[130:131], 11, v[130:131]
	v_lshl_add_u64 v[130:131], v[128:129], 0, v[130:131]
	v_lshl_add_u64 v[236:237], v[130:131], 0, v[238:239]
	global_load_dwordx4 v[180:183], v[236:237], off
	global_load_dwordx4 v[176:179], v[236:237], off offset:256
	v_add_u32_e32 v130, 0x90, v126
	v_ashrrev_i32_e32 v131, 31, v130
	v_lshlrev_b64 v[130:131], 11, v[130:131]
	v_lshl_add_u64 v[130:131], v[128:129], 0, v[130:131]
	v_lshl_add_u64 v[236:237], v[130:131], 0, v[238:239]
	global_load_dwordx4 v[172:175], v[236:237], off
	global_load_dwordx4 v[168:171], v[236:237], off offset:256
	v_add_u32_e32 v130, 0xa0, v126
	v_add_u32_e32 v126, 0xb0, v126
	v_ashrrev_i32_e32 v131, 31, v130
	v_ashrrev_i32_e32 v127, 31, v126
	v_lshlrev_b64 v[130:131], 11, v[130:131]
	v_lshlrev_b64 v[126:127], 11, v[126:127]
	v_lshl_add_u64 v[130:131], v[128:129], 0, v[130:131]
	v_lshl_add_u64 v[126:127], v[128:129], 0, v[126:127]
	v_lshl_add_u64 v[236:237], v[130:131], 0, v[238:239]
	global_load_dwordx4 v[164:167], v[236:237], off
	global_load_dwordx4 v[160:163], v[236:237], off offset:256
	v_lshl_add_u64 v[236:237], v[126:127], 0, v[238:239]
	global_load_dwordx4 v[156:159], v[236:237], off
	global_load_dwordx4 v[152:155], v[236:237], off offset:256
	v_lshl_add_u64 v[126:127], v[150:151], 2, s[22:23]
	global_load_dwordx4 v[142:145], v[126:127], off
	global_load_dwordx4 v[138:141], v[126:127], off offset:64
	global_load_dwordx4 v[130:133], v[126:127], off offset:512
	s_nop 0
	global_load_dwordx4 v[126:129], v[126:127], off offset:576
	v_mul_f32_e32 v147, v135, v135
	v_mul_f32_e32 v148, v137, v137
	v_fmac_f32_e32 v147, v134, v134
	v_fmac_f32_e32 v148, v136, v136
	v_add_f32_e32 v147, v147, v148
	v_mul_f32_e32 v148, v123, v123
	v_mul_f32_e32 v149, v125, v125
	v_fmac_f32_e32 v148, v122, v122
	v_fmac_f32_e32 v149, v124, v124
	v_add_f32_e32 v148, v148, v149
	v_add_f32_e32 v147, v148, v147
	v_mul_f32_e32 v148, v119, v119
	v_mul_f32_e32 v149, v121, v121
	v_fmac_f32_e32 v148, v118, v118
	v_fmac_f32_e32 v149, v120, v120
	v_add_f32_e32 v148, v148, v149
	v_add_f32_e32 v147, v148, v147
	v_mul_f32_e32 v148, v115, v115
	v_mul_f32_e32 v149, v117, v117
	v_fmac_f32_e32 v148, v114, v114
	v_fmac_f32_e32 v149, v116, v116
	v_add_f32_e32 v148, v148, v149
	v_add_f32_e32 v147, v148, v147
	ds_bpermute_b32 v148, v1, v147
	v_and_b32_e32 v224, 63, v146
	s_lshl_b32 s2, s2, 2
	v_cmp_gt_u32_e64 s[4:5], 16, v224
	s_add_i32 s34, s2, 0
	s_waitcnt lgkmcnt(0)
	v_add_f32_e32 v147, v147, v148
	ds_bpermute_b32 v148, v233, v147
	s_and_saveexec_b64 s[2:3], s[4:5]
	s_cbranch_execz .LBB0_478
	s_lshl_b32 s6, s24, 10
	s_add_i32 s6, s34, s6
	v_lshl_add_u32 v149, v217, 4, s6
	s_waitcnt lgkmcnt(0)
	v_add_f32_e32 v147, v147, v148
	ds_write_b32 v149, v147

.LBB0_506:
	s_or_b64 exec, exec, s[2:3]
	s_waitcnt vmcnt(0) lgkmcnt(0)
	s_barrier
	v_permlane16_swap_b32_e32 v212, v214
	v_permlane16_swap_b32_e32 v213, v215
	v_permlane16_swap_b32_e32 v208, v210
	v_permlane16_swap_b32_e32 v209, v211
	v_permlane16_swap_b32_e32 v204, v206
	v_permlane16_swap_b32_e32 v205, v207
	v_permlane16_swap_b32_e32 v200, v202
	v_permlane16_swap_b32_e32 v201, v203
	v_permlane16_swap_b32_e32 v196, v198
	v_permlane16_swap_b32_e32 v197, v199
	v_permlane16_swap_b32_e32 v192, v194
	v_permlane16_swap_b32_e32 v193, v195
	v_permlane16_swap_b32_e32 v188, v190
	v_permlane16_swap_b32_e32 v189, v191
	v_permlane16_swap_b32_e32 v184, v186
	v_permlane16_swap_b32_e32 v185, v187
	v_permlane16_swap_b32_e32 v180, v182
	v_permlane16_swap_b32_e32 v181, v183
	v_permlane16_swap_b32_e32 v176, v178
	v_permlane16_swap_b32_e32 v177, v179
	v_permlane16_swap_b32_e32 v172, v174
	v_permlane16_swap_b32_e32 v173, v175
	v_permlane16_swap_b32_e32 v168, v170
	v_permlane16_swap_b32_e32 v169, v171
	v_permlane16_swap_b32_e32 v164, v166
	v_permlane16_swap_b32_e32 v165, v167
	v_permlane16_swap_b32_e32 v160, v162
	v_permlane16_swap_b32_e32 v161, v163
	v_permlane16_swap_b32_e32 v156, v158
	v_permlane16_swap_b32_e32 v157, v159
	v_permlane16_swap_b32_e32 v152, v154
	v_permlane16_swap_b32_e32 v153, v155
	v_permlane32_swap_b32_e32 v212, v214
	v_permlane32_swap_b32_e32 v213, v215
	v_permlane32_swap_b32_e32 v208, v210
	v_permlane32_swap_b32_e32 v209, v211
	v_permlane32_swap_b32_e32 v204, v206
	v_permlane32_swap_b32_e32 v205, v207
	v_permlane32_swap_b32_e32 v200, v202
	v_permlane32_swap_b32_e32 v201, v203
	v_permlane32_swap_b32_e32 v196, v198
	v_permlane32_swap_b32_e32 v197, v199
	v_permlane32_swap_b32_e32 v192, v194
	v_permlane32_swap_b32_e32 v193, v195
	v_permlane32_swap_b32_e32 v188, v190
	v_permlane32_swap_b32_e32 v189, v191
	v_permlane32_swap_b32_e32 v184, v186
	v_permlane32_swap_b32_e32 v185, v187
	v_permlane32_swap_b32_e32 v180, v182
	v_permlane32_swap_b32_e32 v181, v183
	v_permlane32_swap_b32_e32 v176, v178
	v_permlane32_swap_b32_e32 v177, v179
	v_permlane32_swap_b32_e32 v172, v174
	v_permlane32_swap_b32_e32 v173, v175
	v_permlane32_swap_b32_e32 v168, v170
	v_permlane32_swap_b32_e32 v169, v171
	v_permlane32_swap_b32_e32 v164, v166
	v_permlane32_swap_b32_e32 v165, v167
	v_permlane32_swap_b32_e32 v160, v162
	v_permlane32_swap_b32_e32 v161, v163
	v_permlane32_swap_b32_e32 v156, v158
	v_permlane32_swap_b32_e32 v157, v159
	v_permlane32_swap_b32_e32 v152, v154
	v_permlane32_swap_b32_e32 v153, v155
	v_swap_b32 v212, v214
	v_swap_b32 v213, v215
	v_swap_b32 v208, v210
	v_swap_b32 v209, v211
	v_swap_b32 v204, v206
	v_swap_b32 v205, v207
	v_swap_b32 v200, v202
	v_swap_b32 v201, v203
	v_swap_b32 v196, v198
	v_swap_b32 v197, v199
	v_swap_b32 v192, v194
	v_swap_b32 v193, v195
	v_swap_b32 v188, v190
	v_swap_b32 v189, v191
	v_swap_b32 v184, v186
	v_swap_b32 v185, v187
	v_swap_b32 v180, v182
	v_swap_b32 v181, v183
	v_swap_b32 v176, v178
	v_swap_b32 v177, v179
	v_swap_b32 v172, v174
	v_swap_b32 v173, v175
	v_swap_b32 v168, v170
	v_swap_b32 v169, v171
	v_swap_b32 v164, v166
	v_swap_b32 v165, v167
	v_swap_b32 v160, v162
	v_swap_b32 v161, v163
	v_swap_b32 v156, v158
	v_swap_b32 v157, v159
	v_swap_b32 v152, v154
	v_swap_b32 v153, v155
	v_mov_b32_e32 v146, 0
	ds_read_b32 v147, v146 offset:10240
	v_lshl_add_u32 v146, v222, 2, 0
	s_waitcnt lgkmcnt(0)
	ds_read_b32 v148, v146 offset:8192
	v_add_u32_e32 v218, s33, v222
	v_ashrrev_i32_e32 v219, 31, v218
	s_waitcnt vmcnt(36)
	v_or_b32_e32 v147, v147, v223
	v_lshlrev_b64 v[218:219], 11, v[218:219]
	s_waitcnt vmcnt(35)
	v_lshlrev_b32_e32 v220, 16, v214
	v_and_b32_e32 v221, 0xffff0000, v214
	v_lshlrev_b32_e32 v214, 16, v215
	v_and_b32_e32 v215, 0xffff0000, v215
	s_waitcnt lgkmcnt(0)
	v_pk_mul_f32 v[136:137], v[136:137], v[148:149] op_sel_hi:[1,0]
	v_pk_mul_f32 v[134:135], v[134:135], v[148:149] op_sel_hi:[1,0]
	s_waitcnt vmcnt(3)
	v_pk_fma_f32 v[136:137], v[144:145], v[136:137], v[214:215]
	v_pk_fma_f32 v[220:221], v[142:143], v[134:135], v[220:221]
	v_mov_b32_e32 v134, 0x7fc00000
	v_cmp_ne_u32_e32 vcc, 0, v147
	v_lshl_add_u64 v[214:215], s[0:1], 0, v[218:219]
	v_lshl_add_u64 v[214:215], v[150:151], 1, v[214:215]
	v_cndmask_b32_e32 v135, v136, v134, vcc
	v_cndmask_b32_e32 v147, v137, v134, vcc
	v_cndmask_b32_e32 v149, v220, v134, vcc
	v_cndmask_b32_e32 v216, v221, v134, vcc
	v_cvt_pk_bf16_f32 v136, v149, v216
	v_cvt_pk_bf16_f32 v137, v135, v147
	v_mbcnt_lo_u32_b32 v238, -1, 0
	v_mbcnt_hi_u32_b32 v238, -1, v238
	v_lshrrev_b32_e32 v238, 4, v238
	v_lshlrev_b32_e32 v238, 3, v238
	v_mov_b32_e32 v239, 0
	v_mov_b32_e32 v240, v136
	v_mov_b32_e32 v241, v137
	v_mul_f32_e32 v136, v216, v216
	v_mul_f32_e32 v137, v147, v147
	v_fmac_f32_e32 v136, v149, v149
	v_fmac_f32_e32 v137, v135, v135
	v_add_f32_e32 v135, v136, v137
	v_lshlrev_b32_e32 v136, 16, v212
	v_and_b32_e32 v137, 0xffff0000, v212
	v_pk_mul_f32 v[122:123], v[122:123], v[148:149] op_sel_hi:[1,0]
	v_lshlrev_b32_e32 v212, 16, v213
	v_and_b32_e32 v213, 0xffff0000, v213
	v_pk_mul_f32 v[124:125], v[124:125], v[148:149] op_sel_hi:[1,0]
	s_waitcnt vmcnt(3)
	v_pk_fma_f32 v[122:123], v[138:139], v[122:123], v[136:137]
	v_pk_fma_f32 v[124:125], v[140:141], v[124:125], v[212:213]
	v_cndmask_b32_e32 v123, v123, v134, vcc
	v_cndmask_b32_e32 v147, v124, v134, vcc
	v_cndmask_b32_e32 v149, v125, v134, vcc
	v_cndmask_b32_e32 v124, v122, v134, vcc
	v_cvt_pk_bf16_f32 v122, v124, v123
	v_mul_f32_e32 v123, v123, v123
	v_fmac_f32_e32 v123, v124, v124
	v_mul_f32_e32 v124, v149, v149
	v_fmac_f32_e32 v124, v147, v147
	v_add_f32_e32 v123, v123, v124
	v_lshlrev_b32_e32 v124, 16, v210
	v_and_b32_e32 v125, 0xffff0000, v210
	v_lshlrev_b32_e32 v136, 16, v211
	v_and_b32_e32 v137, 0xffff0000, v211
	v_pk_mul_f32 v[120:121], v[120:121], v[148:149] op_sel_hi:[1,0]
	v_pk_mul_f32 v[118:119], v[118:119], v[148:149] op_sel_hi:[1,0]
	s_waitcnt vmcnt(2)
	v_pk_fma_f32 v[120:121], v[132:133], v[120:121], v[136:137]
	v_pk_fma_f32 v[118:119], v[130:131], v[118:119], v[124:125]
	v_cndmask_b32_e32 v125, v121, v134, vcc
	v_cndmask_b32_e32 v136, v119, v134, vcc
	v_add_f32_e32 v123, v135, v123
	v_cndmask_b32_e32 v124, v120, v134, vcc
	v_cndmask_b32_e32 v135, v118, v134, vcc
	v_mul_f32_e32 v118, v136, v136
	v_mul_f32_e32 v119, v125, v125
	v_fmac_f32_e32 v118, v135, v135
	v_fmac_f32_e32 v119, v124, v124
	v_add_f32_e32 v118, v118, v119
	v_add_f32_e32 v123, v118, v123
	v_lshlrev_b32_e32 v118, 16, v208
	v_and_b32_e32 v119, 0xffff0000, v208
	v_lshlrev_b32_e32 v120, 16, v209
	v_and_b32_e32 v121, 0xffff0000, v209
	v_pk_mul_f32 v[116:117], v[116:117], v[148:149] op_sel_hi:[1,0]
	v_pk_mul_f32 v[114:115], v[114:115], v[148:149] op_sel_hi:[1,0]
	s_waitcnt vmcnt(1)
	v_pk_fma_f32 v[116:117], v[128:129], v[116:117], v[120:121]
	v_pk_fma_f32 v[114:115], v[126:127], v[114:115], v[118:119]
	v_cndmask_b32_e32 v119, v117, v134, vcc
	v_cndmask_b32_e32 v121, v115, v134, vcc
	v_cndmask_b32_e32 v118, v116, v134, vcc
	v_cndmask_b32_e32 v120, v114, v134, vcc
	v_mul_f32_e32 v114, v121, v121
	v_mul_f32_e32 v115, v119, v119
	v_fmac_f32_e32 v114, v120, v120
	v_fmac_f32_e32 v115, v118, v118
	v_add_f32_e32 v114, v114, v115
	v_add_f32_e32 v114, v114, v123
	ds_bpermute_b32 v115, v1, v114
	v_cvt_pk_bf16_f32 v123, v147, v149
	v_mov_b32_e32 v242, v122
	v_mov_b32_e32 v243, v123
	s_nop 1
	v_permlane32_swap_b32_e32 v240, v242
	v_permlane32_swap_b32_e32 v241, v243
	s_nop 0
	v_permlane16_swap_b32_e32 v240, v242
	v_permlane16_swap_b32_e32 v241, v243
	v_lshl_add_u64 v[236:237], v[214:215], 0, v[238:239]
	global_store_dwordx4 v[236:237], v[240:243], off
	v_cvt_pk_bf16_f32 v116, v135, v136
	v_cvt_pk_bf16_f32 v117, v124, v125
	s_waitcnt lgkmcnt(0)
	v_add_f32_e32 v114, v114, v115
	ds_bpermute_b32 v115, v233, v114
	v_mov_b32_e32 v244, v116
	v_mov_b32_e32 v245, v117
	v_cvt_pk_bf16_f32 v116, v120, v121
	v_cvt_pk_bf16_f32 v117, v118, v119
	v_mov_b32_e32 v246, v116
	v_mov_b32_e32 v247, v117
	s_nop 1
	v_permlane32_swap_b32_e32 v244, v246
	v_permlane32_swap_b32_e32 v245, v247
	s_nop 0
	v_permlane16_swap_b32_e32 v244, v246
	v_permlane16_swap_b32_e32 v245, v247
	v_lshl_add_u64 v[236:237], v[214:215], 0, v[238:239]
	global_store_dwordx4 v[236:237], v[244:247], off offset:256
	s_and_saveexec_b64 s[2:3], s[4:5]
	s_cbranch_execz .LBB0_508
	v_lshl_add_u32 v116, v222, 4, s34
	s_waitcnt lgkmcnt(0)
	v_add_f32_e32 v114, v114, v115
	ds_write_b32 v116, v114 offset:16384
